# final LayerNorm pass de-serialised: gamma/beta resident in registers, next row prefetched, no per-chunk vmcnt(0) drains
# speedup vs baseline: 1.0101x; 1.0061x over previous
; __device__ __forceinline__ unsigned pk2(float lo, float hi) { return cvt_pk_bf16(lo, hi); }
; #define lane (pg8::pg8_lane_id())
; __device__ __forceinline__ void ln_pass(float* z, const float* g, const float* b, bf16_t* xb, int wave, int lane) {
;     const int gw = blockIdx.x * 8 + wave, NGW = gridDim.x * 8;
;     for (int row = gw; row < R; row += NGW) {
;         f32x4* p = (f32x4*)(z + (size_t)row * DM) + lane;
;         f32x4 v[8]; float s = 0.f;
; #pragma unroll
;         for (int j = 0; j < 8; ++j) { v[j] = p[64 * j]; s += (v[j][0] + v[j][1]) + (v[j][2] + v[j][3]); }
;         const float mean = wave_sum(s) * (1.0f / DM); float s2 = 0.f;
; #pragma unroll
;         for (int j = 0; j < 8; ++j) { v[j] = v[j] - mean; s2 += (v[j][0] * v[j][0] + v[j][1] * v[j][1]) + (v[j][2] * v[j][2] + v[j][3] * v[j][3]); }
;         const float rstd = 1.0f / sqrtf(wave_sum(s2) * (1.0f / DM) + LN_EPS);
; #pragma unroll
;         for (int j = 0; j < 8; ++j) { const int col = 4 * lane + 256 * j; const f32x4 gg = *(const f32x4*)(g + col), bb = *(const f32x4*)(b + col);
;             const f32x4 o = v[j] * rstd * gg + bb; if (xb) p[64 * j] = o; else __builtin_nontemporal_store(o, p + 64 * j);
;             if (xb) { u32x2 w; w.x = pk2(o[0], o[1]); w.y = pk2(o[2], o[3]); *(u32x2*)(xb + (size_t)row * DM + col) = w; } }
.LBB0_1746:
	s_or_b64 exec, exec, s[2:3]
	s_cmp_gt_i32 s34, 0xbfff
	s_waitcnt lgkmcnt(0)
	s_barrier
	v_mbcnt_lo_u32_b32 v0, -1, 0
	v_mbcnt_hi_u32_b32 v0, -1, v0
	s_cbranch_scc1 .LBB0_1749
	v_mbcnt_hi_u32_b32 v2, -1, v254
	v_and_b32_e32 v3, 64, v2
	v_add_u32_e32 v3, 64, v3
	v_xor_b32_e32 v4, 1, v2
	v_cmp_lt_i32_e32 vcc, v4, v3
	s_load_dwordx4 s[4:7], s[0:1], 0x90
	s_load_dwordx2 s[2:3], s[0:1], 0xb0
	v_cndmask_b32_e32 v4, v2, v4, vcc
	v_lshlrev_b32_e32 v54, 2, v4
	v_xor_b32_e32 v4, 2, v2
	v_cmp_lt_i32_e32 vcc, v4, v3
	s_mov_b64 s[0:1], 0x2000
	s_ashr_i32 s35, s34, 31
	v_cndmask_b32_e32 v4, v2, v4, vcc
	v_lshlrev_b32_e32 v55, 2, v4
	v_xor_b32_e32 v4, 4, v2
	v_cmp_lt_i32_e32 vcc, v4, v3
	v_ashrrev_i32_e32 v1, 31, v0
	v_mov_b32_e32 v60, 0x3727c5ac
	v_cndmask_b32_e32 v4, v2, v4, vcc
	v_lshlrev_b32_e32 v56, 2, v4
	v_xor_b32_e32 v4, 8, v2
	v_cmp_lt_i32_e32 vcc, v4, v3
	v_mov_b32_e32 v61, 0x260
	s_nop 0
	v_cndmask_b32_e32 v4, v2, v4, vcc
	v_lshlrev_b32_e32 v57, 2, v4
	v_xor_b32_e32 v4, 16, v2
	v_cmp_lt_i32_e32 vcc, v4, v3
	s_nop 1
	v_cndmask_b32_e32 v4, v2, v4, vcc
	v_lshlrev_b32_e32 v58, 2, v4
	v_xor_b32_e32 v4, 32, v2
	v_cmp_lt_i32_e32 vcc, v4, v3
	s_nop 1
	v_cndmask_b32_e32 v2, v2, v4, vcc
	v_lshlrev_b32_e32 v59, 2, v2
	v_lshlrev_b32_e32 v2, 2, v0
	v_ashrrev_i32_e32 v3, 31, v2
	v_lshlrev_b64 v[2:3], 2, v[2:3]
	s_waitcnt lgkmcnt(0)
	v_lshl_add_u64 v[4:5], s[4:5], 0, v[2:3]
	v_lshl_add_u64 v[2:3], s[6:7], 0, v[2:3]
	v_lshl_add_u64 v[32:33], v[4:5], 0, s[0:1]
	v_lshl_add_u64 v[34:35], v[2:3], 0, s[0:1]
	s_mov_b64 s[0:1], 0x3000
	v_lshl_add_u64 v[36:37], v[4:5], 0, s[0:1]
	v_lshl_add_u64 v[38:39], v[2:3], 0, s[0:1]
	s_mov_b64 s[0:1], 0x3400
	v_lshl_add_u64 v[40:41], v[4:5], 0, s[0:1]
	v_lshl_add_u64 v[42:43], v[2:3], 0, s[0:1]
	s_mov_b64 s[0:1], 0x3800
	v_lshl_add_u64 v[44:45], v[4:5], 0, s[0:1]
	v_lshl_add_u64 v[46:47], v[2:3], 0, s[0:1]
	s_mov_b64 s[0:1], 0x3c00
	v_lshl_add_u64 v[48:49], v[4:5], 0, s[0:1]
	v_lshl_add_u64 v[50:51], v[2:3], 0, s[0:1]
	s_lshl_b64 s[0:1], s[34:35], 13
	s_add_u32 s0, s2, s0
	s_addc_u32 s1, s3, s1
	v_lshl_add_u64 v[0:1], v[0:1], 4, s[0:1]
	s_mov_b64 s[0:1], 0x1000
	s_ashr_i32 s37, s36, 31
	v_lshl_add_u64 v[52:53], v[0:1], 0, s[0:1]
	s_lshl_b64 s[2:3], s[36:37], 13
	s_mov_b32 s4, 0xf800000
	global_load_dwordx4 v[100:103], v[32:33], off
	global_load_dwordx4 v[132:135], v[34:35], off
	global_load_dwordx4 v[104:107], v[32:33], off offset:1024
	global_load_dwordx4 v[136:139], v[34:35], off offset:1024
	global_load_dwordx4 v[108:111], v[32:33], off offset:2048
	global_load_dwordx4 v[140:143], v[34:35], off offset:2048
	global_load_dwordx4 v[112:115], v[32:33], off offset:3072
	global_load_dwordx4 v[144:147], v[34:35], off offset:3072
	global_load_dwordx4 v[116:119], v[36:37], off
	global_load_dwordx4 v[148:151], v[38:39], off
	global_load_dwordx4 v[120:123], v[40:41], off
	global_load_dwordx4 v[152:155], v[42:43], off
	global_load_dwordx4 v[124:127], v[44:45], off
	global_load_dwordx4 v[156:159], v[46:47], off
	global_load_dwordx4 v[128:131], v[48:49], off
	global_load_dwordx4 v[160:163], v[50:51], off
	global_load_dwordx4 v[164:167], v[52:53], off offset:-4096
	global_load_dwordx4 v[168:171], v[52:53], off offset:-3072
	global_load_dwordx4 v[172:175], v[52:53], off offset:-2048
	global_load_dwordx4 v[176:179], v[52:53], off offset:-1024
	global_load_dwordx4 v[180:183], v[52:53], off
	global_load_dwordx4 v[184:187], v[52:53], off offset:1024
	global_load_dwordx4 v[188:191], v[52:53], off offset:2048
	global_load_dwordx4 v[192:195], v[52:53], off offset:3072
	s_waitcnt vmcnt(0)
	s_branch .Lln_entry
.LBB0_1748:
	s_waitcnt vmcnt(8)
.Lln_entry:
	v_mov_b64_e32 v[28:29], v[164:165]
	v_mov_b64_e32 v[30:31], v[166:167]
	v_mov_b64_e32 v[20:21], v[168:169]
	v_mov_b64_e32 v[22:23], v[170:171]
	v_mov_b64_e32 v[24:25], v[172:173]
	v_mov_b64_e32 v[26:27], v[174:175]
	v_mov_b64_e32 v[16:17], v[176:177]
	v_mov_b64_e32 v[18:19], v[178:179]
	v_mov_b64_e32 v[12:13], v[180:181]
	v_mov_b64_e32 v[14:15], v[182:183]
	v_mov_b64_e32 v[8:9], v[184:185]
	v_mov_b64_e32 v[10:11], v[186:187]
	v_mov_b64_e32 v[4:5], v[188:189]
	v_mov_b64_e32 v[6:7], v[190:191]
	v_mov_b64_e32 v[0:1], v[192:193]
	v_mov_b64_e32 v[2:3], v[194:195]
	s_add_i32 s34, s34, s36
	s_cmp_lt_i32 s34, 0xc000
	s_cbranch_scc0 .Lln_nopf
	v_lshl_add_u64 v[196:197], v[52:53], 0, s[2:3]
	global_load_dwordx4 v[164:167], v[196:197], off offset:-4096
	global_load_dwordx4 v[168:171], v[196:197], off offset:-3072
	global_load_dwordx4 v[172:175], v[196:197], off offset:-2048
	global_load_dwordx4 v[176:179], v[196:197], off offset:-1024
	global_load_dwordx4 v[180:183], v[196:197], off
	global_load_dwordx4 v[184:187], v[196:197], off offset:1024
	global_load_dwordx4 v[188:191], v[196:197], off offset:2048
	global_load_dwordx4 v[192:195], v[196:197], off offset:3072
; __device__ __forceinline__ void ln_pass(float* z, const float* g, const float* b, bf16_t* xb, int wave, int lane) {
;     ...
;         f32x4 v[8]; float s = 0.f;
; #pragma unroll
;         for (int j = 0; j < 8; ++j) { v[j] = p[64 * j]; s += (v[j][0] + v[j][1]) + (v[j][2] + v[j][3]); }
;         const float mean = wave_sum(s) * (1.0f / DM); float s2 = 0.f;
; #pragma unroll
;         for (int j = 0; j < 8; ++j) { v[j] = v[j] - mean; s2 += (v[j][0] * v[j][0] + v[j][1] * v[j][1]) + (v[j][2] * v[j][2] + v[j][3] * v[j][3]); }
;         const float rstd = 1.0f / sqrtf(wave_sum(s2) * (1.0f / DM) + LN_EPS);
.Lln_nopf:
	v_mov_b32_e32 v62, v28
	v_mov_b32_e32 v63, v20
	v_mov_b32_e32 v64, v29
	v_mov_b32_e32 v65, v21
	v_mov_b32_e32 v66, v30
	v_mov_b32_e32 v67, v22
	v_mov_b32_e32 v68, v31
	v_mov_b32_e32 v69, v23
	v_mov_b32_e32 v70, v25
	v_mov_b32_e32 v71, v26
	v_mov_b32_e32 v72, v24
	v_mov_b32_e32 v73, v27
	v_pk_add_f32 v[62:63], v[62:63], v[64:65]
	v_pk_add_f32 v[64:65], v[66:67], v[68:69]
	v_pk_add_f32 v[66:67], v[70:71], v[72:73]
	v_pk_add_f32 v[62:63], v[62:63], v[64:65]
	v_pk_add_f32 v[64:65], v[66:67], v[66:67] op_sel:[0,1] op_sel_hi:[1,0]
	v_add_f32_e32 v62, 0, v62
	v_add_f32_e32 v74, v16, v17
	v_add_f32_e32 v76, v18, v19
	v_mov_b32_e32 v79, v12
	v_mov_b32_e32 v75, v14
	v_mov_b32_e32 v77, v15
	v_mov_b32_e32 v65, v13
	v_add_f32_e32 v78, v62, v63
	v_mov_b32_e32 v80, v9
	v_mov_b32_e32 v81, v10
	v_mov_b32_e32 v82, v8
	v_mov_b32_e32 v83, v11
	v_pk_add_f32 v[68:69], v[74:75], v[76:77]
	v_pk_add_f32 v[62:63], v[78:79], v[64:65]
	v_pk_add_f32 v[70:71], v[80:81], v[82:83]
	v_pk_add_f32 v[62:63], v[62:63], v[68:69]
	v_pk_add_f32 v[66:67], v[70:71], v[70:71] op_sel:[0,1] op_sel_hi:[1,0]
	v_pk_add_f32 v[62:63], v[62:63], v[62:63] op_sel:[0,1] op_sel_hi:[1,0]
	v_add_f32_e32 v84, v4, v5
	v_add_f32_e32 v86, v6, v7
	v_mov_b32_e32 v85, v2
	v_mov_b32_e32 v87, v3
	v_mov_b32_e32 v67, v1
	v_mov_b32_e32 v63, v0
	v_pk_add_f32 v[72:73], v[84:85], v[86:87]
	v_pk_add_f32 v[62:63], v[62:63], v[66:67]
	s_nop 0
	v_pk_add_f32 v[62:63], v[62:63], v[72:73]
	s_nop 0
	v_add_f32_e32 v62, v62, v63
	ds_bpermute_b32 v63, v54, v62
	s_waitcnt lgkmcnt(0)
	v_add_f32_e32 v62, v62, v63
	ds_bpermute_b32 v63, v55, v62
	s_waitcnt lgkmcnt(0)
	v_add_f32_e32 v62, v62, v63
	ds_bpermute_b32 v63, v56, v62
	s_waitcnt lgkmcnt(0)
	v_add_f32_e32 v62, v62, v63
	ds_bpermute_b32 v63, v57, v62
	s_waitcnt lgkmcnt(0)
	v_add_f32_e32 v62, v62, v63
	ds_bpermute_b32 v63, v58, v62
	s_waitcnt lgkmcnt(0)
	v_add_f32_e32 v62, v62, v63
	ds_bpermute_b32 v63, v59, v62
	s_waitcnt lgkmcnt(0)
	v_add_f32_e32 v85, v62, v63
	v_fmamk_f32 v31, v85, 0xba000000, v31
	v_fmamk_f32 v29, v85, 0xba000000, v29
	v_fmamk_f32 v23, v85, 0xba000000, v23
	v_fmamk_f32 v21, v85, 0xba000000, v21
	v_fmamk_f32 v30, v85, 0xba000000, v30
	v_fmac_f32_e32 v28, 0xba000000, v85
	v_fmamk_f32 v22, v85, 0xba000000, v22
	v_fmac_f32_e32 v20, 0xba000000, v85
	v_fmamk_f32 v25, v85, 0xba000000, v25
	v_fmamk_f32 v24, v85, 0xba000000, v24
	v_fmamk_f32 v27, v85, 0xba000000, v27
	v_fmac_f32_e32 v26, 0xba000000, v85
	v_mov_b32_e32 v64, v29
	v_mov_b32_e32 v65, v21
	v_mov_b32_e32 v68, v31
	v_mov_b32_e32 v69, v23
	v_mov_b32_e32 v62, v28
	v_mov_b32_e32 v63, v20
	v_mov_b32_e32 v66, v30
	v_mov_b32_e32 v67, v22
	v_pk_mul_f32 v[70:71], v[26:27], v[26:27]
	v_pk_mul_f32 v[72:73], v[24:25], v[24:25]
	v_pk_mul_f32 v[64:65], v[64:65], v[64:65]
	v_pk_mul_f32 v[68:69], v[68:69], v[68:69]
	v_fmamk_f32 v16, v85, 0xba000000, v16
	v_fmac_f32_e32 v18, 0xba000000, v85
	v_pk_mov_b32 v[86:87], v[72:73], v[70:71] op_sel:[1,0]
	v_mov_b32_e32 v73, v71
	v_pk_fma_f32 v[62:63], v[62:63], v[62:63], v[64:65]
	v_pk_fma_f32 v[64:65], v[66:67], v[66:67], v[68:69]
	v_fmamk_f32 v17, v85, 0xba000000, v17
	v_fmamk_f32 v19, v85, 0xba000000, v19
	v_mul_f32_e32 v74, v16, v16
	v_mul_f32_e32 v76, v18, v18
	v_pk_add_f32 v[66:67], v[86:87], v[72:73]
	v_pk_add_f32 v[62:63], v[62:63], v[64:65]
	v_fmamk_f32 v15, v85, 0xba000000, v15
	v_fmamk_f32 v14, v85, 0xba000000, v14
	v_fmamk_f32 v13, v85, 0xba000000, v13
	v_fmac_f32_e32 v12, 0xba000000, v85
	v_fmamk_f32 v9, v85, 0xba000000, v9
	v_fmamk_f32 v8, v85, 0xba000000, v8
	v_fmamk_f32 v11, v85, 0xba000000, v11
	v_fmac_f32_e32 v10, 0xba000000, v85
	v_pk_fma_f32 v[70:71], v[16:17], v[16:17], v[74:75] op_sel_hi:[1,1,0]
	v_pk_fma_f32 v[74:75], v[18:19], v[18:19], v[76:77] op_sel_hi:[1,1,0]
	v_pk_add_f32 v[64:65], v[66:67], v[66:67] op_sel_hi:[0,1]
	v_pk_add_f32 v[62:63], v[62:63], v[62:63] op_sel_hi:[0,1]
	v_pk_mul_f32 v[78:79], v[10:11], v[10:11]
	v_pk_mul_f32 v[80:81], v[8:9], v[8:9]
	v_mul_f32_e32 v70, v12, v12
	v_mul_f32_e32 v74, v13, v13
	v_mul_f32_e32 v64, v14, v14
	v_mul_f32_e32 v62, v15, v15
	v_pk_mov_b32 v[76:77], v[80:81], v[78:79] op_sel:[1,0]
	v_mov_b32_e32 v81, v79
	v_pk_add_f32 v[66:67], v[70:71], v[74:75]
	v_pk_add_f32 v[62:63], v[64:65], v[62:63]
	v_pk_add_f32 v[68:69], v[76:77], v[80:81]
	v_pk_add_f32 v[62:63], v[66:67], v[62:63]
	v_pk_add_f32 v[70:71], v[68:69], v[68:69] op_sel_hi:[0,1]
	v_pk_add_f32 v[72:73], v[62:63], v[62:63] op_sel_hi:[0,1]
	v_fmamk_f32 v4, v85, 0xba000000, v4
	v_fmac_f32_e32 v6, 0xba000000, v85
	v_fmamk_f32 v5, v85, 0xba000000, v5
	v_fmamk_f32 v7, v85, 0xba000000, v7
	v_mul_f32_e32 v82, v4, v4
	v_mul_f32_e32 v84, v6, v6
	v_fmamk_f32 v3, v85, 0xba000000, v3
	v_fmamk_f32 v2, v85, 0xba000000, v2
	v_fmamk_f32 v1, v85, 0xba000000, v1
	v_pk_fma_f32 v[78:79], v[4:5], v[4:5], v[82:83] op_sel_hi:[1,1,0]
	v_pk_fma_f32 v[82:83], v[6:7], v[6:7], v[84:85] op_sel_hi:[1,1,0]
	v_fmac_f32_e32 v0, 0xba000000, v85
	v_mul_f32_e32 v78, v0, v0
	v_mul_f32_e32 v82, v1, v1
	v_mul_f32_e32 v70, v2, v2
	v_mul_f32_e32 v72, v3, v3
	v_pk_add_f32 v[74:75], v[78:79], v[82:83]
	v_pk_add_f32 v[70:71], v[70:71], v[72:73]
	s_nop 0
	v_pk_add_f32 v[70:71], v[74:75], v[70:71]
	s_nop 0
	v_add_f32_e32 v70, v70, v71
	ds_bpermute_b32 v71, v54, v70
	s_waitcnt lgkmcnt(0)
; __device__ __forceinline__ unsigned pk2(float lo, float hi) { return cvt_pk_bf16(lo, hi); }
; #define lane (pg8::pg8_lane_id())
; __device__ __forceinline__ void ln_pass(float* z, const float* g, const float* b, bf16_t* xb, int wave, int lane) {
;     ...
;         const float rstd = 1.0f / sqrtf(wave_sum(s2) * (1.0f / DM) + LN_EPS);
; #pragma unroll
;         for (int j = 0; j < 8; ++j) { const int col = 4 * lane + 256 * j; const f32x4 gg = *(const f32x4*)(g + col), bb = *(const f32x4*)(b + col);
;             const f32x4 o = v[j] * rstd * gg + bb; if (xb) p[64 * j] = o; else __builtin_nontemporal_store(o, p + 64 * j);
;             if (xb) { u32x2 w; w.x = pk2(o[0], o[1]); w.y = pk2(o[2], o[3]); *(u32x2*)(xb + (size_t)row * DM + col) = w; } }
	v_add_f32_e32 v70, v70, v71
	ds_bpermute_b32 v71, v55, v70
	s_waitcnt lgkmcnt(0)
	v_add_f32_e32 v70, v70, v71
	ds_bpermute_b32 v71, v56, v70
	s_waitcnt lgkmcnt(0)
	v_add_f32_e32 v70, v70, v71
	ds_bpermute_b32 v71, v57, v70
	s_waitcnt lgkmcnt(0)
	v_add_f32_e32 v70, v70, v71
	ds_bpermute_b32 v71, v58, v70
	s_waitcnt lgkmcnt(0)
	v_add_f32_e32 v70, v70, v71
	ds_bpermute_b32 v71, v59, v70
	s_waitcnt lgkmcnt(0)
	v_add_f32_e32 v70, v70, v71
	v_fmamk_f32 v70, v70, 0x3a000000, v60
	v_mul_f32_e32 v71, 0x4f800000, v70
	v_cmp_gt_f32_e32 vcc, s4, v70
	s_nop 1
	v_cndmask_b32_e32 v70, v70, v71, vcc
	v_sqrt_f32_e32 v71, v70
	s_nop 0
	v_add_u32_e32 v72, -1, v71
	v_add_u32_e32 v73, 1, v71
	v_fma_f32 v74, -v72, v71, v70
	v_fma_f32 v75, -v73, v71, v70
	v_cmp_ge_f32_e64 s[0:1], 0, v74
	s_nop 1
	v_cndmask_b32_e64 v71, v71, v72, s[0:1]
	v_cmp_lt_f32_e64 s[0:1], 0, v75
	s_nop 1
	v_cndmask_b32_e64 v71, v71, v73, s[0:1]
	v_mul_f32_e32 v72, 0x37800000, v71
	v_cndmask_b32_e32 v71, v71, v72, vcc
	v_cmp_class_f32_e32 vcc, v70, v61
	s_nop 1
	v_cndmask_b32_e32 v70, v71, v70, vcc
	v_div_scale_f32 v71, s[0:1], v70, v70, 1.0
	v_rcp_f32_e32 v72, v71
	v_div_scale_f32 v73, vcc, 1.0, v70, 1.0
	v_fma_f32 v74, -v71, v72, 1.0
	v_fmac_f32_e32 v72, v74, v72
	v_mul_f32_e32 v74, v73, v72
	v_fma_f32 v75, -v71, v74, v73
	v_fmac_f32_e32 v74, v75, v72
	v_fma_f32 v71, -v71, v74, v73
	v_div_fmas_f32 v71, v71, v72, v74
	v_div_fixup_f32 v70, v71, v70, 1.0
	v_pk_mul_f32 v[28:29], v[28:29], v[70:71] op_sel_hi:[1,0]
	v_pk_mul_f32 v[30:31], v[30:31], v[70:71] op_sel_hi:[1,0]
	v_pk_mul_f32 v[22:23], v[22:23], v[70:71] op_sel_hi:[1,0]
	v_pk_mul_f32 v[20:21], v[20:21], v[70:71] op_sel_hi:[1,0]
	v_pk_mul_f32 v[26:27], v[26:27], v[70:71] op_sel_hi:[1,0]
	v_pk_mul_f32 v[24:25], v[24:25], v[70:71] op_sel_hi:[1,0]
	v_pk_mul_f32 v[18:19], v[18:19], v[70:71] op_sel_hi:[1,0]
	v_pk_mul_f32 v[16:17], v[16:17], v[70:71] op_sel_hi:[1,0]
	v_pk_mul_f32 v[14:15], v[14:15], v[70:71] op_sel_hi:[1,0]
	v_pk_mul_f32 v[12:13], v[12:13], v[70:71] op_sel_hi:[1,0]
	v_pk_mul_f32 v[10:11], v[10:11], v[70:71] op_sel_hi:[1,0]
	v_pk_mul_f32 v[8:9], v[8:9], v[70:71] op_sel_hi:[1,0]
	v_pk_mul_f32 v[6:7], v[6:7], v[70:71] op_sel_hi:[1,0]
	v_pk_mul_f32 v[4:5], v[4:5], v[70:71] op_sel_hi:[1,0]
	v_pk_mul_f32 v[2:3], v[2:3], v[70:71] op_sel_hi:[1,0]
	v_pk_mul_f32 v[0:1], v[0:1], v[70:71] op_sel_hi:[1,0]
	v_pk_fma_f32 v[28:29], v[100:101], v[28:29], v[132:133]
	v_pk_fma_f32 v[30:31], v[102:103], v[30:31], v[134:135]
	global_store_dwordx4 v[52:53], v[28:31], off offset:-4096 nt
	v_pk_fma_f32 v[20:21], v[104:105], v[20:21], v[136:137]
	v_pk_fma_f32 v[22:23], v[106:107], v[22:23], v[138:139]
	global_store_dwordx4 v[52:53], v[20:23], off offset:-3072 nt
	v_pk_fma_f32 v[24:25], v[108:109], v[24:25], v[140:141]
	v_pk_fma_f32 v[26:27], v[110:111], v[26:27], v[142:143]
	global_store_dwordx4 v[52:53], v[24:27], off offset:-2048 nt
	v_pk_fma_f32 v[16:17], v[112:113], v[16:17], v[144:145]
	v_pk_fma_f32 v[18:19], v[114:115], v[18:19], v[146:147]
	global_store_dwordx4 v[52:53], v[16:19], off offset:-1024 nt
	v_pk_fma_f32 v[12:13], v[116:117], v[12:13], v[148:149]
	v_pk_fma_f32 v[14:15], v[118:119], v[14:15], v[150:151]
	global_store_dwordx4 v[52:53], v[12:15], off nt
	v_pk_fma_f32 v[8:9], v[120:121], v[8:9], v[152:153]
	v_pk_fma_f32 v[10:11], v[122:123], v[10:11], v[154:155]
	global_store_dwordx4 v[52:53], v[8:11], off offset:1024 nt
	v_pk_fma_f32 v[4:5], v[124:125], v[4:5], v[156:157]
	v_pk_fma_f32 v[6:7], v[126:127], v[6:7], v[158:159]
	global_store_dwordx4 v[52:53], v[4:7], off offset:2048 nt
	v_pk_fma_f32 v[0:1], v[128:129], v[0:1], v[160:161]
	v_pk_fma_f32 v[2:3], v[130:131], v[2:3], v[162:163]
	global_store_dwordx4 v[52:53], v[0:3], off offset:3072 nt
	v_lshl_add_u64 v[52:53], v[52:53], 0, s[2:3]
	s_cbranch_scc1 .LBB0_1748
